# pooling unit LDS fill: 40 masked row loads per thread issued back-to-back into own registers, one wait, then the 40 masked ds_writes (was 40 serialized load/wait/write round trips)
# speedup vs baseline: 1.0302x; 1.0091x over previous
; __global__ void __launch_bounds__(NWAVES * 64, 2) mega_fwd(Args args) {
;     ...
; #pragma unroll 8
;                     for (int it = 0; it < 40; ++it) { const int e = tidp + it * 512; const int r = e >> 8, cq = e & 255, sr_ = s0 - 8 + r;
;                         if (e < 79 * 256 && sr_ >= 0 && sr_ < S_) ubuf[e] = *(const unsigned*)(sq + (size_t)sr_ * INC + 2 * cq); }
.LBB0_443:
	v_ashrrev_i32_e32 v75, 8, v4
	v_add_u32_e32 v75, v14, v75
	v_cmp_gt_i32_e32 vcc, s67, v4
	v_cmp_gt_i32_e64 s[36:37], s68, v75
	v_cmp_lt_i32_e64 s[0:1], -1, v75
	s_and_b64 s[6:7], vcc, s[36:37]
	s_and_b64 s[6:7], s[6:7], s[0:1]
	s_and_saveexec_b64 s[0:1], s[6:7]
	v_mad_u64_u32 v[76:77], s[6:7], v75, s18, v[2:3]
	global_load_dword v78, v[76:77], off
	s_or_b64 exec, exec, s[0:1]
	v_add_u32_e32 v76, 0x200, v4
	v_ashrrev_i32_e32 v75, 8, v76
	v_add_u32_e32 v75, v14, v75
	v_cmp_gt_i32_e32 vcc, s67, v76
	v_cmp_gt_i32_e64 s[36:37], s68, v75
	v_cmp_lt_i32_e64 s[0:1], -1, v75
	s_and_b64 s[6:7], vcc, s[36:37]
	s_and_b64 s[6:7], s[6:7], s[0:1]
	s_and_saveexec_b64 s[0:1], s[6:7]
	v_mad_u64_u32 v[76:77], s[6:7], v75, s18, v[2:3]
	global_load_dword v79, v[76:77], off
	s_or_b64 exec, exec, s[0:1]
	v_add_u32_e32 v76, 0x400, v4
	v_ashrrev_i32_e32 v75, 8, v76
	v_add_u32_e32 v75, v14, v75
	v_cmp_gt_i32_e32 vcc, s67, v76
	v_cmp_gt_i32_e64 s[36:37], s68, v75
	v_cmp_lt_i32_e64 s[0:1], -1, v75
	s_and_b64 s[6:7], vcc, s[36:37]
	s_and_b64 s[6:7], s[6:7], s[0:1]
	s_and_saveexec_b64 s[0:1], s[6:7]
	v_mad_u64_u32 v[76:77], s[6:7], v75, s18, v[2:3]
	global_load_dword v80, v[76:77], off
	s_or_b64 exec, exec, s[0:1]
	v_add_u32_e32 v76, 0x600, v4
	v_ashrrev_i32_e32 v75, 8, v76
	v_add_u32_e32 v75, v14, v75
	v_cmp_gt_i32_e32 vcc, s67, v76
	v_cmp_gt_i32_e64 s[36:37], s68, v75
	v_cmp_lt_i32_e64 s[0:1], -1, v75
	s_and_b64 s[6:7], vcc, s[36:37]
	s_and_b64 s[6:7], s[6:7], s[0:1]
	s_and_saveexec_b64 s[0:1], s[6:7]
	v_mad_u64_u32 v[76:77], s[6:7], v75, s18, v[2:3]
	global_load_dword v81, v[76:77], off
	s_or_b64 exec, exec, s[0:1]
	v_add_u32_e32 v76, 0x800, v4
	v_ashrrev_i32_e32 v75, 8, v76
	v_add_u32_e32 v75, v14, v75
	v_cmp_gt_i32_e32 vcc, s67, v76
	v_cmp_gt_i32_e64 s[36:37], s68, v75
	v_cmp_lt_i32_e64 s[0:1], -1, v75
	s_and_b64 s[6:7], vcc, s[36:37]
	s_and_b64 s[6:7], s[6:7], s[0:1]
	s_and_saveexec_b64 s[0:1], s[6:7]
	v_mad_u64_u32 v[76:77], s[6:7], v75, s18, v[2:3]
	global_load_dword v82, v[76:77], off
	s_or_b64 exec, exec, s[0:1]
	v_add_u32_e32 v76, 0xa00, v4
	v_ashrrev_i32_e32 v75, 8, v76
	v_add_u32_e32 v75, v14, v75
	v_cmp_gt_i32_e32 vcc, s67, v76
	v_cmp_gt_i32_e64 s[36:37], s68, v75
	v_cmp_lt_i32_e64 s[0:1], -1, v75
	s_and_b64 s[6:7], vcc, s[36:37]
	s_and_b64 s[6:7], s[6:7], s[0:1]
	s_and_saveexec_b64 s[0:1], s[6:7]
	v_mad_u64_u32 v[76:77], s[6:7], v75, s18, v[2:3]
	global_load_dword v83, v[76:77], off
	s_or_b64 exec, exec, s[0:1]
	v_add_u32_e32 v76, 0xc00, v4
	v_ashrrev_i32_e32 v75, 8, v76
	v_add_u32_e32 v75, v14, v75
	v_cmp_gt_i32_e32 vcc, s67, v76
	v_cmp_gt_i32_e64 s[36:37], s68, v75
	v_cmp_lt_i32_e64 s[0:1], -1, v75
	s_and_b64 s[6:7], vcc, s[36:37]
	s_and_b64 s[6:7], s[6:7], s[0:1]
	s_and_saveexec_b64 s[0:1], s[6:7]
	v_mad_u64_u32 v[76:77], s[6:7], v75, s18, v[2:3]
	global_load_dword v84, v[76:77], off
	s_or_b64 exec, exec, s[0:1]
	v_add_u32_e32 v76, 0xe00, v4
	v_ashrrev_i32_e32 v75, 8, v76
	v_add_u32_e32 v75, v14, v75
	v_cmp_gt_i32_e32 vcc, s67, v76
	v_cmp_gt_i32_e64 s[36:37], s68, v75
	v_cmp_lt_i32_e64 s[0:1], -1, v75
	s_and_b64 s[6:7], vcc, s[36:37]
	s_and_b64 s[6:7], s[6:7], s[0:1]
	s_and_saveexec_b64 s[0:1], s[6:7]
	v_mad_u64_u32 v[76:77], s[6:7], v75, s18, v[2:3]
	global_load_dword v85, v[76:77], off
	s_or_b64 exec, exec, s[0:1]
	v_add_u32_e32 v76, 0x1000, v4
	v_ashrrev_i32_e32 v75, 8, v76
	v_add_u32_e32 v75, v14, v75
	v_cmp_gt_i32_e32 vcc, s67, v76
	v_cmp_gt_i32_e64 s[36:37], s68, v75
	v_cmp_lt_i32_e64 s[0:1], -1, v75
	s_and_b64 s[6:7], vcc, s[36:37]
	s_and_b64 s[6:7], s[6:7], s[0:1]
	s_and_saveexec_b64 s[0:1], s[6:7]
	v_mad_u64_u32 v[76:77], s[6:7], v75, s18, v[2:3]
	global_load_dword v86, v[76:77], off
	s_or_b64 exec, exec, s[0:1]
	v_add_u32_e32 v76, 0x1200, v4
	v_ashrrev_i32_e32 v75, 8, v76
	v_add_u32_e32 v75, v14, v75
	v_cmp_gt_i32_e32 vcc, s67, v76
	v_cmp_gt_i32_e64 s[36:37], s68, v75
	v_cmp_lt_i32_e64 s[0:1], -1, v75
	s_and_b64 s[6:7], vcc, s[36:37]
	s_and_b64 s[6:7], s[6:7], s[0:1]
	s_and_saveexec_b64 s[0:1], s[6:7]
	v_mad_u64_u32 v[76:77], s[6:7], v75, s18, v[2:3]
	global_load_dword v87, v[76:77], off
	s_or_b64 exec, exec, s[0:1]
	v_add_u32_e32 v76, 0x1400, v4
	v_ashrrev_i32_e32 v75, 8, v76
	v_add_u32_e32 v75, v14, v75
	v_cmp_gt_i32_e32 vcc, s67, v76
	v_cmp_gt_i32_e64 s[36:37], s68, v75
	v_cmp_lt_i32_e64 s[0:1], -1, v75
	s_and_b64 s[6:7], vcc, s[36:37]
	s_and_b64 s[6:7], s[6:7], s[0:1]
	s_and_saveexec_b64 s[0:1], s[6:7]
	v_mad_u64_u32 v[76:77], s[6:7], v75, s18, v[2:3]
	global_load_dword v88, v[76:77], off
	s_or_b64 exec, exec, s[0:1]
	v_add_u32_e32 v76, 0x1600, v4
	v_ashrrev_i32_e32 v75, 8, v76
	v_add_u32_e32 v75, v14, v75
	v_cmp_gt_i32_e32 vcc, s67, v76
	v_cmp_gt_i32_e64 s[36:37], s68, v75
	v_cmp_lt_i32_e64 s[0:1], -1, v75
	s_and_b64 s[6:7], vcc, s[36:37]
	s_and_b64 s[6:7], s[6:7], s[0:1]
	s_and_saveexec_b64 s[0:1], s[6:7]
	v_mad_u64_u32 v[76:77], s[6:7], v75, s18, v[2:3]
	global_load_dword v89, v[76:77], off
	s_or_b64 exec, exec, s[0:1]
	v_add_u32_e32 v76, 0x1800, v4
	v_ashrrev_i32_e32 v75, 8, v76
	v_add_u32_e32 v75, v14, v75
	v_cmp_gt_i32_e32 vcc, s67, v76
	v_cmp_gt_i32_e64 s[36:37], s68, v75
	v_cmp_lt_i32_e64 s[0:1], -1, v75
	s_and_b64 s[6:7], vcc, s[36:37]
	s_and_b64 s[6:7], s[6:7], s[0:1]
	s_and_saveexec_b64 s[0:1], s[6:7]
	v_mad_u64_u32 v[76:77], s[6:7], v75, s18, v[2:3]
	global_load_dword v90, v[76:77], off
	s_or_b64 exec, exec, s[0:1]
	v_add_u32_e32 v76, 0x1a00, v4
	v_ashrrev_i32_e32 v75, 8, v76
	v_add_u32_e32 v75, v14, v75
	v_cmp_gt_i32_e32 vcc, s67, v76
	v_cmp_gt_i32_e64 s[36:37], s68, v75
	v_cmp_lt_i32_e64 s[0:1], -1, v75
	s_and_b64 s[6:7], vcc, s[36:37]
	s_and_b64 s[6:7], s[6:7], s[0:1]
	s_and_saveexec_b64 s[0:1], s[6:7]
; __global__ void __launch_bounds__(NWAVES * 64, 2) mega_fwd(Args args) {
;     ...
; #pragma unroll 8
;                     for (int it = 0; it < 40; ++it) { const int e = tidp + it * 512; const int r = e >> 8, cq = e & 255, sr_ = s0 - 8 + r;
;                         if (e < 79 * 256 && sr_ >= 0 && sr_ < S_) ubuf[e] = *(const unsigned*)(sq + (size_t)sr_ * INC + 2 * cq); }
	v_mad_u64_u32 v[76:77], s[6:7], v75, s18, v[2:3]
	global_load_dword v91, v[76:77], off
	s_or_b64 exec, exec, s[0:1]
	v_add_u32_e32 v76, 0x1c00, v4
	v_ashrrev_i32_e32 v75, 8, v76
	v_add_u32_e32 v75, v14, v75
	v_cmp_gt_i32_e32 vcc, s67, v76
	v_cmp_gt_i32_e64 s[36:37], s68, v75
	v_cmp_lt_i32_e64 s[0:1], -1, v75
	s_and_b64 s[6:7], vcc, s[36:37]
	s_and_b64 s[6:7], s[6:7], s[0:1]
	s_and_saveexec_b64 s[0:1], s[6:7]
	v_mad_u64_u32 v[76:77], s[6:7], v75, s18, v[2:3]
	global_load_dword v92, v[76:77], off
	s_or_b64 exec, exec, s[0:1]
	v_add_u32_e32 v76, 0x1e00, v4
	v_ashrrev_i32_e32 v75, 8, v76
	v_add_u32_e32 v75, v14, v75
	v_cmp_gt_i32_e32 vcc, s67, v76
	v_cmp_gt_i32_e64 s[36:37], s68, v75
	v_cmp_lt_i32_e64 s[0:1], -1, v75
	s_and_b64 s[6:7], vcc, s[36:37]
	s_and_b64 s[6:7], s[6:7], s[0:1]
	s_and_saveexec_b64 s[0:1], s[6:7]
	v_mad_u64_u32 v[76:77], s[6:7], v75, s18, v[2:3]
	global_load_dword v93, v[76:77], off
	s_or_b64 exec, exec, s[0:1]
	v_add_u32_e32 v76, 0x2000, v4
	v_ashrrev_i32_e32 v75, 8, v76
	v_add_u32_e32 v75, v14, v75
	v_cmp_gt_i32_e32 vcc, s67, v76
	v_cmp_gt_i32_e64 s[36:37], s68, v75
	v_cmp_lt_i32_e64 s[0:1], -1, v75
	s_and_b64 s[6:7], vcc, s[36:37]
	s_and_b64 s[6:7], s[6:7], s[0:1]
	s_and_saveexec_b64 s[0:1], s[6:7]
	v_mad_u64_u32 v[76:77], s[6:7], v75, s18, v[2:3]
	global_load_dword v94, v[76:77], off
	s_or_b64 exec, exec, s[0:1]
	v_add_u32_e32 v76, 0x2200, v4
	v_ashrrev_i32_e32 v75, 8, v76
	v_add_u32_e32 v75, v14, v75
	v_cmp_gt_i32_e32 vcc, s67, v76
	v_cmp_gt_i32_e64 s[36:37], s68, v75
	v_cmp_lt_i32_e64 s[0:1], -1, v75
	s_and_b64 s[6:7], vcc, s[36:37]
	s_and_b64 s[6:7], s[6:7], s[0:1]
	s_and_saveexec_b64 s[0:1], s[6:7]
	v_mad_u64_u32 v[76:77], s[6:7], v75, s18, v[2:3]
	global_load_dword v95, v[76:77], off
	s_or_b64 exec, exec, s[0:1]
	v_add_u32_e32 v76, 0x2400, v4
	v_ashrrev_i32_e32 v75, 8, v76
	v_add_u32_e32 v75, v14, v75
	v_cmp_gt_i32_e32 vcc, s67, v76
	v_cmp_gt_i32_e64 s[36:37], s68, v75
	v_cmp_lt_i32_e64 s[0:1], -1, v75
	s_and_b64 s[6:7], vcc, s[36:37]
	s_and_b64 s[6:7], s[6:7], s[0:1]
	s_and_saveexec_b64 s[0:1], s[6:7]
	v_mad_u64_u32 v[76:77], s[6:7], v75, s18, v[2:3]
	global_load_dword v98, v[76:77], off
	s_or_b64 exec, exec, s[0:1]
	v_add_u32_e32 v76, 0x2600, v4
	v_ashrrev_i32_e32 v75, 8, v76
	v_add_u32_e32 v75, v14, v75
	v_cmp_gt_i32_e32 vcc, s67, v76
	v_cmp_gt_i32_e64 s[36:37], s68, v75
	v_cmp_lt_i32_e64 s[0:1], -1, v75
	s_and_b64 s[6:7], vcc, s[36:37]
	s_and_b64 s[6:7], s[6:7], s[0:1]
	s_and_saveexec_b64 s[0:1], s[6:7]
	v_mad_u64_u32 v[76:77], s[6:7], v75, s18, v[2:3]
	global_load_dword v99, v[76:77], off
	s_or_b64 exec, exec, s[0:1]
	v_add_u32_e32 v76, 0x2800, v4
	v_ashrrev_i32_e32 v75, 8, v76
	v_add_u32_e32 v75, v14, v75
	v_cmp_gt_i32_e32 vcc, s67, v76
	v_cmp_gt_i32_e64 s[36:37], s68, v75
	v_cmp_lt_i32_e64 s[0:1], -1, v75
	s_and_b64 s[6:7], vcc, s[36:37]
	s_and_b64 s[6:7], s[6:7], s[0:1]
	s_and_saveexec_b64 s[0:1], s[6:7]
	v_mad_u64_u32 v[76:77], s[6:7], v75, s18, v[2:3]
	global_load_dword v100, v[76:77], off
	s_or_b64 exec, exec, s[0:1]
	v_add_u32_e32 v76, 0x2a00, v4
	v_ashrrev_i32_e32 v75, 8, v76
	v_add_u32_e32 v75, v14, v75
	v_cmp_gt_i32_e32 vcc, s67, v76
	v_cmp_gt_i32_e64 s[36:37], s68, v75
	v_cmp_lt_i32_e64 s[0:1], -1, v75
	s_and_b64 s[6:7], vcc, s[36:37]
	s_and_b64 s[6:7], s[6:7], s[0:1]
	s_and_saveexec_b64 s[0:1], s[6:7]
	v_mad_u64_u32 v[76:77], s[6:7], v75, s18, v[2:3]
	global_load_dword v101, v[76:77], off
	s_or_b64 exec, exec, s[0:1]
	v_add_u32_e32 v76, 0x2c00, v4
	v_ashrrev_i32_e32 v75, 8, v76
	v_add_u32_e32 v75, v14, v75
	v_cmp_gt_i32_e32 vcc, s67, v76
	v_cmp_gt_i32_e64 s[36:37], s68, v75
	v_cmp_lt_i32_e64 s[0:1], -1, v75
	s_and_b64 s[6:7], vcc, s[36:37]
	s_and_b64 s[6:7], s[6:7], s[0:1]
	s_and_saveexec_b64 s[0:1], s[6:7]
	v_mad_u64_u32 v[76:77], s[6:7], v75, s18, v[2:3]
	global_load_dword v102, v[76:77], off
	s_or_b64 exec, exec, s[0:1]
	v_add_u32_e32 v76, 0x2e00, v4
	v_ashrrev_i32_e32 v75, 8, v76
	v_add_u32_e32 v75, v14, v75
	v_cmp_gt_i32_e32 vcc, s67, v76
	v_cmp_gt_i32_e64 s[36:37], s68, v75
	v_cmp_lt_i32_e64 s[0:1], -1, v75
	s_and_b64 s[6:7], vcc, s[36:37]
	s_and_b64 s[6:7], s[6:7], s[0:1]
	s_and_saveexec_b64 s[0:1], s[6:7]
	v_mad_u64_u32 v[76:77], s[6:7], v75, s18, v[2:3]
	global_load_dword v103, v[76:77], off
	s_or_b64 exec, exec, s[0:1]
	s_waitcnt vmcnt(24)
; __global__ void __launch_bounds__(NWAVES * 64, 2) mega_fwd(Args args) {
;     ...
; #pragma unroll 8
;                     for (int it = 0; it < 40; ++it) { const int e = tidp + it * 512; const int r = e >> 8, cq = e & 255, sr_ = s0 - 8 + r;
;                         if (e < 79 * 256 && sr_ >= 0 && sr_ < S_) ubuf[e] = *(const unsigned*)(sq + (size_t)sr_ * INC + 2 * cq); }
	v_add_u32_e32 v76, 0x3000, v4
	v_ashrrev_i32_e32 v75, 8, v76
	v_add_u32_e32 v75, v14, v75
	v_cmp_gt_i32_e32 vcc, s67, v76
	v_cmp_gt_i32_e64 s[36:37], s68, v75
	v_cmp_lt_i32_e64 s[0:1], -1, v75
	s_and_b64 s[6:7], vcc, s[36:37]
	s_and_b64 s[6:7], s[6:7], s[0:1]
	s_and_saveexec_b64 s[0:1], s[6:7]
	v_mad_u64_u32 v[76:77], s[6:7], v75, s18, v[2:3]
	global_load_dword v104, v[76:77], off
	s_or_b64 exec, exec, s[0:1]
	v_add_u32_e32 v76, 0x3200, v4
	v_ashrrev_i32_e32 v75, 8, v76
	v_add_u32_e32 v75, v14, v75
	v_cmp_gt_i32_e32 vcc, s67, v76
	v_cmp_gt_i32_e64 s[36:37], s68, v75
	v_cmp_lt_i32_e64 s[0:1], -1, v75
	s_and_b64 s[6:7], vcc, s[36:37]
	s_and_b64 s[6:7], s[6:7], s[0:1]
	s_and_saveexec_b64 s[0:1], s[6:7]
	v_mad_u64_u32 v[76:77], s[6:7], v75, s18, v[2:3]
	global_load_dword v105, v[76:77], off
	s_or_b64 exec, exec, s[0:1]
	v_add_u32_e32 v76, 0x3400, v4
	v_ashrrev_i32_e32 v75, 8, v76
	v_add_u32_e32 v75, v14, v75
	v_cmp_gt_i32_e32 vcc, s67, v76
	v_cmp_gt_i32_e64 s[36:37], s68, v75
	v_cmp_lt_i32_e64 s[0:1], -1, v75
	s_and_b64 s[6:7], vcc, s[36:37]
	s_and_b64 s[6:7], s[6:7], s[0:1]
	s_and_saveexec_b64 s[0:1], s[6:7]
	v_mad_u64_u32 v[76:77], s[6:7], v75, s18, v[2:3]
	global_load_dword v106, v[76:77], off
	s_or_b64 exec, exec, s[0:1]
	v_add_u32_e32 v76, 0x3600, v4
	v_ashrrev_i32_e32 v75, 8, v76
	v_add_u32_e32 v75, v14, v75
	v_cmp_gt_i32_e32 vcc, s67, v76
	v_cmp_gt_i32_e64 s[36:37], s68, v75
	v_cmp_lt_i32_e64 s[0:1], -1, v75
	s_and_b64 s[6:7], vcc, s[36:37]
	s_and_b64 s[6:7], s[6:7], s[0:1]
	s_and_saveexec_b64 s[0:1], s[6:7]
	v_mad_u64_u32 v[76:77], s[6:7], v75, s18, v[2:3]
	global_load_dword v107, v[76:77], off
	s_or_b64 exec, exec, s[0:1]
	v_add_u32_e32 v76, 0x3800, v4
	v_ashrrev_i32_e32 v75, 8, v76
	v_add_u32_e32 v75, v14, v75
	v_cmp_gt_i32_e32 vcc, s67, v76
	v_cmp_gt_i32_e64 s[36:37], s68, v75
	v_cmp_lt_i32_e64 s[0:1], -1, v75
	s_and_b64 s[6:7], vcc, s[36:37]
	s_and_b64 s[6:7], s[6:7], s[0:1]
	s_and_saveexec_b64 s[0:1], s[6:7]
	v_mad_u64_u32 v[76:77], s[6:7], v75, s18, v[2:3]
	global_load_dword v108, v[76:77], off
	s_or_b64 exec, exec, s[0:1]
	v_add_u32_e32 v76, 0x3a00, v4
	v_ashrrev_i32_e32 v75, 8, v76
	v_add_u32_e32 v75, v14, v75
	v_cmp_gt_i32_e32 vcc, s67, v76
	v_cmp_gt_i32_e64 s[36:37], s68, v75
	v_cmp_lt_i32_e64 s[0:1], -1, v75
	s_and_b64 s[6:7], vcc, s[36:37]
	s_and_b64 s[6:7], s[6:7], s[0:1]
	s_and_saveexec_b64 s[0:1], s[6:7]
	v_mad_u64_u32 v[76:77], s[6:7], v75, s18, v[2:3]
	global_load_dword v109, v[76:77], off
	s_or_b64 exec, exec, s[0:1]
	v_add_u32_e32 v76, 0x3c00, v4
	v_ashrrev_i32_e32 v75, 8, v76
	v_add_u32_e32 v75, v14, v75
	v_cmp_gt_i32_e32 vcc, s67, v76
	v_cmp_gt_i32_e64 s[36:37], s68, v75
	v_cmp_lt_i32_e64 s[0:1], -1, v75
	s_and_b64 s[6:7], vcc, s[36:37]
	s_and_b64 s[6:7], s[6:7], s[0:1]
	s_and_saveexec_b64 s[0:1], s[6:7]
	v_mad_u64_u32 v[76:77], s[6:7], v75, s18, v[2:3]
	global_load_dword v110, v[76:77], off
	s_or_b64 exec, exec, s[0:1]
	v_add_u32_e32 v76, 0x3e00, v4
	v_ashrrev_i32_e32 v75, 8, v76
	v_add_u32_e32 v75, v14, v75
	v_cmp_gt_i32_e32 vcc, s67, v76
	v_cmp_gt_i32_e64 s[36:37], s68, v75
	v_cmp_lt_i32_e64 s[0:1], -1, v75
	s_and_b64 s[6:7], vcc, s[36:37]
	s_and_b64 s[6:7], s[6:7], s[0:1]
	s_and_saveexec_b64 s[0:1], s[6:7]
	v_mad_u64_u32 v[76:77], s[6:7], v75, s18, v[2:3]
	global_load_dword v111, v[76:77], off
	s_or_b64 exec, exec, s[0:1]
	v_add_u32_e32 v76, 0x4000, v4
	v_ashrrev_i32_e32 v75, 8, v76
	v_add_u32_e32 v75, v14, v75
	v_cmp_gt_i32_e32 vcc, s67, v76
	v_cmp_gt_i32_e64 s[36:37], s68, v75
	v_cmp_lt_i32_e64 s[0:1], -1, v75
	s_and_b64 s[6:7], vcc, s[36:37]
	s_and_b64 s[6:7], s[6:7], s[0:1]
	s_and_saveexec_b64 s[0:1], s[6:7]
	v_mad_u64_u32 v[76:77], s[6:7], v75, s18, v[2:3]
	global_load_dword v112, v[76:77], off
	s_or_b64 exec, exec, s[0:1]
	v_add_u32_e32 v76, 0x4200, v4
	v_ashrrev_i32_e32 v75, 8, v76
	v_add_u32_e32 v75, v14, v75
	v_cmp_gt_i32_e32 vcc, s67, v76
	v_cmp_gt_i32_e64 s[36:37], s68, v75
	v_cmp_lt_i32_e64 s[0:1], -1, v75
	s_and_b64 s[6:7], vcc, s[36:37]
	s_and_b64 s[6:7], s[6:7], s[0:1]
	s_and_saveexec_b64 s[0:1], s[6:7]
	v_mad_u64_u32 v[76:77], s[6:7], v75, s18, v[2:3]
	global_load_dword v113, v[76:77], off
	s_or_b64 exec, exec, s[0:1]
	v_add_u32_e32 v76, 0x4400, v4
	v_ashrrev_i32_e32 v75, 8, v76
	v_add_u32_e32 v75, v14, v75
	v_cmp_gt_i32_e32 vcc, s67, v76
	v_cmp_gt_i32_e64 s[36:37], s68, v75
	v_cmp_lt_i32_e64 s[0:1], -1, v75
	s_and_b64 s[6:7], vcc, s[36:37]
	s_and_b64 s[6:7], s[6:7], s[0:1]
	s_and_saveexec_b64 s[0:1], s[6:7]
	v_mad_u64_u32 v[76:77], s[6:7], v75, s18, v[2:3]
	global_load_dword v114, v[76:77], off
	s_or_b64 exec, exec, s[0:1]
	v_add_u32_e32 v76, 0x4600, v4
	v_ashrrev_i32_e32 v75, 8, v76
	v_add_u32_e32 v75, v14, v75
	v_cmp_gt_i32_e32 vcc, s67, v76
	v_cmp_gt_i32_e64 s[36:37], s68, v75
	v_cmp_lt_i32_e64 s[0:1], -1, v75
	s_and_b64 s[6:7], vcc, s[36:37]
	s_and_b64 s[6:7], s[6:7], s[0:1]
	s_and_saveexec_b64 s[0:1], s[6:7]
	v_mad_u64_u32 v[76:77], s[6:7], v75, s18, v[2:3]
	global_load_dword v115, v[76:77], off
	s_or_b64 exec, exec, s[0:1]
	v_add_u32_e32 v76, 0x4800, v4
	v_ashrrev_i32_e32 v75, 8, v76
	v_add_u32_e32 v75, v14, v75
	v_cmp_gt_i32_e32 vcc, s67, v76
	v_cmp_gt_i32_e64 s[36:37], s68, v75
	v_cmp_lt_i32_e64 s[0:1], -1, v75
	s_and_b64 s[6:7], vcc, s[36:37]
	s_and_b64 s[6:7], s[6:7], s[0:1]
	s_and_saveexec_b64 s[0:1], s[6:7]
	v_mad_u64_u32 v[76:77], s[6:7], v75, s18, v[2:3]
	global_load_dword v132, v[76:77], off
	s_or_b64 exec, exec, s[0:1]
	v_add_u32_e32 v76, 0x4a00, v4
	v_ashrrev_i32_e32 v75, 8, v76
	v_add_u32_e32 v75, v14, v75
	v_cmp_gt_i32_e32 vcc, s67, v76
	v_cmp_gt_i32_e64 s[36:37], s68, v75
	v_cmp_lt_i32_e64 s[0:1], -1, v75
	s_and_b64 s[6:7], vcc, s[36:37]
	s_and_b64 s[6:7], s[6:7], s[0:1]
	s_and_saveexec_b64 s[0:1], s[6:7]
	v_mad_u64_u32 v[76:77], s[6:7], v75, s18, v[2:3]
	global_load_dword v133, v[76:77], off
	s_or_b64 exec, exec, s[0:1]
	v_add_u32_e32 v76, 0x4c00, v4
	v_ashrrev_i32_e32 v75, 8, v76
	v_add_u32_e32 v75, v14, v75
	v_cmp_gt_i32_e32 vcc, s67, v76
	v_cmp_gt_i32_e64 s[36:37], s68, v75
	v_cmp_lt_i32_e64 s[0:1], -1, v75
	s_and_b64 s[6:7], vcc, s[36:37]
	s_and_b64 s[6:7], s[6:7], s[0:1]
	s_and_saveexec_b64 s[0:1], s[6:7]
	v_mad_u64_u32 v[76:77], s[6:7], v75, s18, v[2:3]
	global_load_dword v134, v[76:77], off
	s_or_b64 exec, exec, s[0:1]
	v_add_u32_e32 v76, 0x4e00, v4
	v_ashrrev_i32_e32 v75, 8, v76
	v_add_u32_e32 v75, v14, v75
	v_cmp_gt_i32_e32 vcc, s67, v76
	v_cmp_gt_i32_e64 s[36:37], s68, v75
	v_cmp_lt_i32_e64 s[0:1], -1, v75
	s_and_b64 s[6:7], vcc, s[36:37]
	s_and_b64 s[6:7], s[6:7], s[0:1]
	s_and_saveexec_b64 s[0:1], s[6:7]
	v_mad_u64_u32 v[76:77], s[6:7], v75, s18, v[2:3]
	global_load_dword v135, v[76:77], off
	s_or_b64 exec, exec, s[0:1]
	s_waitcnt vmcnt(0)
; __global__ void __launch_bounds__(NWAVES * 64, 2) mega_fwd(Args args) {
;     ...
; #pragma unroll 8
;                     for (int it = 0; it < 40; ++it) { const int e = tidp + it * 512; const int r = e >> 8, cq = e & 255, sr_ = s0 - 8 + r;
;                         if (e < 79 * 256 && sr_ >= 0 && sr_ < S_) ubuf[e] = *(const unsigned*)(sq + (size_t)sr_ * INC + 2 * cq); }
	v_ashrrev_i32_e32 v75, 8, v4
	v_add_u32_e32 v75, v14, v75
	v_cmp_gt_i32_e32 vcc, s67, v4
	v_cmp_gt_i32_e64 s[36:37], s68, v75
	v_cmp_lt_i32_e64 s[0:1], -1, v75
	s_and_b64 s[6:7], vcc, s[36:37]
	s_and_b64 s[6:7], s[6:7], s[0:1]
	s_and_saveexec_b64 s[0:1], s[6:7]
	ds_write_b32 v73, v78
	s_or_b64 exec, exec, s[0:1]
	v_add_u32_e32 v76, 0x200, v4
	v_ashrrev_i32_e32 v75, 8, v76
	v_add_u32_e32 v75, v14, v75
	v_cmp_gt_i32_e32 vcc, s67, v76
	v_cmp_gt_i32_e64 s[36:37], s68, v75
	v_cmp_lt_i32_e64 s[0:1], -1, v75
	s_and_b64 s[6:7], vcc, s[36:37]
	s_and_b64 s[6:7], s[6:7], s[0:1]
	s_and_saveexec_b64 s[0:1], s[6:7]
	ds_write_b32 v73, v79 offset:2048
	s_or_b64 exec, exec, s[0:1]
	v_add_u32_e32 v76, 0x400, v4
	v_ashrrev_i32_e32 v75, 8, v76
	v_add_u32_e32 v75, v14, v75
	v_cmp_gt_i32_e32 vcc, s67, v76
	v_cmp_gt_i32_e64 s[36:37], s68, v75
	v_cmp_lt_i32_e64 s[0:1], -1, v75
	s_and_b64 s[6:7], vcc, s[36:37]
	s_and_b64 s[6:7], s[6:7], s[0:1]
	s_and_saveexec_b64 s[0:1], s[6:7]
	ds_write_b32 v73, v80 offset:4096
	s_or_b64 exec, exec, s[0:1]
	v_add_u32_e32 v76, 0x600, v4
	v_ashrrev_i32_e32 v75, 8, v76
	v_add_u32_e32 v75, v14, v75
	v_cmp_gt_i32_e32 vcc, s67, v76
	v_cmp_gt_i32_e64 s[36:37], s68, v75
	v_cmp_lt_i32_e64 s[0:1], -1, v75
	s_and_b64 s[6:7], vcc, s[36:37]
	s_and_b64 s[6:7], s[6:7], s[0:1]
	s_and_saveexec_b64 s[0:1], s[6:7]
	ds_write_b32 v73, v81 offset:6144
	s_or_b64 exec, exec, s[0:1]
	v_add_u32_e32 v76, 0x800, v4
	v_ashrrev_i32_e32 v75, 8, v76
	v_add_u32_e32 v75, v14, v75
	v_cmp_gt_i32_e32 vcc, s67, v76
	v_cmp_gt_i32_e64 s[36:37], s68, v75
	v_cmp_lt_i32_e64 s[0:1], -1, v75
	s_and_b64 s[6:7], vcc, s[36:37]
	s_and_b64 s[6:7], s[6:7], s[0:1]
	s_and_saveexec_b64 s[0:1], s[6:7]
	ds_write_b32 v73, v82 offset:8192
	s_or_b64 exec, exec, s[0:1]
	v_add_u32_e32 v76, 0xa00, v4
	v_ashrrev_i32_e32 v75, 8, v76
	v_add_u32_e32 v75, v14, v75
	v_cmp_gt_i32_e32 vcc, s67, v76
	v_cmp_gt_i32_e64 s[36:37], s68, v75
	v_cmp_lt_i32_e64 s[0:1], -1, v75
	s_and_b64 s[6:7], vcc, s[36:37]
	s_and_b64 s[6:7], s[6:7], s[0:1]
	s_and_saveexec_b64 s[0:1], s[6:7]
	ds_write_b32 v73, v83 offset:10240
	s_or_b64 exec, exec, s[0:1]
	v_add_u32_e32 v76, 0xc00, v4
	v_ashrrev_i32_e32 v75, 8, v76
	v_add_u32_e32 v75, v14, v75
	v_cmp_gt_i32_e32 vcc, s67, v76
	v_cmp_gt_i32_e64 s[36:37], s68, v75
	v_cmp_lt_i32_e64 s[0:1], -1, v75
	s_and_b64 s[6:7], vcc, s[36:37]
	s_and_b64 s[6:7], s[6:7], s[0:1]
	s_and_saveexec_b64 s[0:1], s[6:7]
	ds_write_b32 v73, v84 offset:12288
	s_or_b64 exec, exec, s[0:1]
	v_add_u32_e32 v76, 0xe00, v4
	v_ashrrev_i32_e32 v75, 8, v76
	v_add_u32_e32 v75, v14, v75
	v_cmp_gt_i32_e32 vcc, s67, v76
	v_cmp_gt_i32_e64 s[36:37], s68, v75
	v_cmp_lt_i32_e64 s[0:1], -1, v75
	s_and_b64 s[6:7], vcc, s[36:37]
	s_and_b64 s[6:7], s[6:7], s[0:1]
	s_and_saveexec_b64 s[0:1], s[6:7]
	ds_write_b32 v73, v85 offset:14336
	s_or_b64 exec, exec, s[0:1]
	v_add_u32_e32 v73, 0x4000, v73
	v_add_u32_e32 v76, 0x1000, v4
	v_ashrrev_i32_e32 v75, 8, v76
	v_add_u32_e32 v75, v14, v75
	v_cmp_gt_i32_e32 vcc, s67, v76
	v_cmp_gt_i32_e64 s[36:37], s68, v75
	v_cmp_lt_i32_e64 s[0:1], -1, v75
	s_and_b64 s[6:7], vcc, s[36:37]
	s_and_b64 s[6:7], s[6:7], s[0:1]
	s_and_saveexec_b64 s[0:1], s[6:7]
	ds_write_b32 v73, v86
	s_or_b64 exec, exec, s[0:1]
	v_add_u32_e32 v76, 0x1200, v4
	v_ashrrev_i32_e32 v75, 8, v76
	v_add_u32_e32 v75, v14, v75
	v_cmp_gt_i32_e32 vcc, s67, v76
	v_cmp_gt_i32_e64 s[36:37], s68, v75
	v_cmp_lt_i32_e64 s[0:1], -1, v75
	s_and_b64 s[6:7], vcc, s[36:37]
	s_and_b64 s[6:7], s[6:7], s[0:1]
	s_and_saveexec_b64 s[0:1], s[6:7]
	ds_write_b32 v73, v87 offset:2048
	s_or_b64 exec, exec, s[0:1]
	v_add_u32_e32 v76, 0x1400, v4
	v_ashrrev_i32_e32 v75, 8, v76
	v_add_u32_e32 v75, v14, v75
	v_cmp_gt_i32_e32 vcc, s67, v76
	v_cmp_gt_i32_e64 s[36:37], s68, v75
	v_cmp_lt_i32_e64 s[0:1], -1, v75
	s_and_b64 s[6:7], vcc, s[36:37]
	s_and_b64 s[6:7], s[6:7], s[0:1]
	s_and_saveexec_b64 s[0:1], s[6:7]
	ds_write_b32 v73, v88 offset:4096
	s_or_b64 exec, exec, s[0:1]
	v_add_u32_e32 v76, 0x1600, v4
	v_ashrrev_i32_e32 v75, 8, v76
	v_add_u32_e32 v75, v14, v75
	v_cmp_gt_i32_e32 vcc, s67, v76
	v_cmp_gt_i32_e64 s[36:37], s68, v75
	v_cmp_lt_i32_e64 s[0:1], -1, v75
	s_and_b64 s[6:7], vcc, s[36:37]
	s_and_b64 s[6:7], s[6:7], s[0:1]
	s_and_saveexec_b64 s[0:1], s[6:7]
	ds_write_b32 v73, v89 offset:6144
	s_or_b64 exec, exec, s[0:1]
	v_add_u32_e32 v76, 0x1800, v4
	v_ashrrev_i32_e32 v75, 8, v76
	v_add_u32_e32 v75, v14, v75
	v_cmp_gt_i32_e32 vcc, s67, v76
	v_cmp_gt_i32_e64 s[36:37], s68, v75
	v_cmp_lt_i32_e64 s[0:1], -1, v75
	s_and_b64 s[6:7], vcc, s[36:37]
	s_and_b64 s[6:7], s[6:7], s[0:1]
	s_and_saveexec_b64 s[0:1], s[6:7]
	ds_write_b32 v73, v90 offset:8192
	s_or_b64 exec, exec, s[0:1]
	v_add_u32_e32 v76, 0x1a00, v4
	v_ashrrev_i32_e32 v75, 8, v76
	v_add_u32_e32 v75, v14, v75
	v_cmp_gt_i32_e32 vcc, s67, v76
	v_cmp_gt_i32_e64 s[36:37], s68, v75
	v_cmp_lt_i32_e64 s[0:1], -1, v75
	s_and_b64 s[6:7], vcc, s[36:37]
	s_and_b64 s[6:7], s[6:7], s[0:1]
	s_and_saveexec_b64 s[0:1], s[6:7]
	ds_write_b32 v73, v91 offset:10240
	s_or_b64 exec, exec, s[0:1]
	v_add_u32_e32 v76, 0x1c00, v4
	v_ashrrev_i32_e32 v75, 8, v76
	v_add_u32_e32 v75, v14, v75
	v_cmp_gt_i32_e32 vcc, s67, v76
	v_cmp_gt_i32_e64 s[36:37], s68, v75
	v_cmp_lt_i32_e64 s[0:1], -1, v75
	s_and_b64 s[6:7], vcc, s[36:37]
	s_and_b64 s[6:7], s[6:7], s[0:1]
	s_and_saveexec_b64 s[0:1], s[6:7]
	ds_write_b32 v73, v92 offset:12288
	s_or_b64 exec, exec, s[0:1]
	v_add_u32_e32 v76, 0x1e00, v4
	v_ashrrev_i32_e32 v75, 8, v76
	v_add_u32_e32 v75, v14, v75
	v_cmp_gt_i32_e32 vcc, s67, v76
	v_cmp_gt_i32_e64 s[36:37], s68, v75
	v_cmp_lt_i32_e64 s[0:1], -1, v75
	s_and_b64 s[6:7], vcc, s[36:37]
	s_and_b64 s[6:7], s[6:7], s[0:1]
; __global__ void __launch_bounds__(NWAVES * 64, 2) mega_fwd(Args args) {
;     ...
; #pragma unroll 8
;                     for (int it = 0; it < 40; ++it) { const int e = tidp + it * 512; const int r = e >> 8, cq = e & 255, sr_ = s0 - 8 + r;
;                         if (e < 79 * 256 && sr_ >= 0 && sr_ < S_) ubuf[e] = *(const unsigned*)(sq + (size_t)sr_ * INC + 2 * cq); }
	s_and_saveexec_b64 s[0:1], s[6:7]
	ds_write_b32 v73, v93 offset:14336
	s_or_b64 exec, exec, s[0:1]
	v_add_u32_e32 v73, 0x4000, v73
	v_add_u32_e32 v76, 0x2000, v4
	v_ashrrev_i32_e32 v75, 8, v76
	v_add_u32_e32 v75, v14, v75
	v_cmp_gt_i32_e32 vcc, s67, v76
	v_cmp_gt_i32_e64 s[36:37], s68, v75
	v_cmp_lt_i32_e64 s[0:1], -1, v75
	s_and_b64 s[6:7], vcc, s[36:37]
	s_and_b64 s[6:7], s[6:7], s[0:1]
	s_and_saveexec_b64 s[0:1], s[6:7]
	ds_write_b32 v73, v94
	s_or_b64 exec, exec, s[0:1]
	v_add_u32_e32 v76, 0x2200, v4
	v_ashrrev_i32_e32 v75, 8, v76
	v_add_u32_e32 v75, v14, v75
	v_cmp_gt_i32_e32 vcc, s67, v76
	v_cmp_gt_i32_e64 s[36:37], s68, v75
	v_cmp_lt_i32_e64 s[0:1], -1, v75
	s_and_b64 s[6:7], vcc, s[36:37]
	s_and_b64 s[6:7], s[6:7], s[0:1]
	s_and_saveexec_b64 s[0:1], s[6:7]
	ds_write_b32 v73, v95 offset:2048
	s_or_b64 exec, exec, s[0:1]
	v_add_u32_e32 v76, 0x2400, v4
	v_ashrrev_i32_e32 v75, 8, v76
	v_add_u32_e32 v75, v14, v75
	v_cmp_gt_i32_e32 vcc, s67, v76
	v_cmp_gt_i32_e64 s[36:37], s68, v75
	v_cmp_lt_i32_e64 s[0:1], -1, v75
	s_and_b64 s[6:7], vcc, s[36:37]
	s_and_b64 s[6:7], s[6:7], s[0:1]
	s_and_saveexec_b64 s[0:1], s[6:7]
	ds_write_b32 v73, v98 offset:4096
	s_or_b64 exec, exec, s[0:1]
	v_add_u32_e32 v76, 0x2600, v4
	v_ashrrev_i32_e32 v75, 8, v76
	v_add_u32_e32 v75, v14, v75
	v_cmp_gt_i32_e32 vcc, s67, v76
	v_cmp_gt_i32_e64 s[36:37], s68, v75
	v_cmp_lt_i32_e64 s[0:1], -1, v75
	s_and_b64 s[6:7], vcc, s[36:37]
	s_and_b64 s[6:7], s[6:7], s[0:1]
	s_and_saveexec_b64 s[0:1], s[6:7]
	ds_write_b32 v73, v99 offset:6144
	s_or_b64 exec, exec, s[0:1]
	v_add_u32_e32 v76, 0x2800, v4
	v_ashrrev_i32_e32 v75, 8, v76
	v_add_u32_e32 v75, v14, v75
	v_cmp_gt_i32_e32 vcc, s67, v76
	v_cmp_gt_i32_e64 s[36:37], s68, v75
	v_cmp_lt_i32_e64 s[0:1], -1, v75
	s_and_b64 s[6:7], vcc, s[36:37]
	s_and_b64 s[6:7], s[6:7], s[0:1]
	s_and_saveexec_b64 s[0:1], s[6:7]
	ds_write_b32 v73, v100 offset:8192
	s_or_b64 exec, exec, s[0:1]
	v_add_u32_e32 v76, 0x2a00, v4
	v_ashrrev_i32_e32 v75, 8, v76
	v_add_u32_e32 v75, v14, v75
	v_cmp_gt_i32_e32 vcc, s67, v76
	v_cmp_gt_i32_e64 s[36:37], s68, v75
	v_cmp_lt_i32_e64 s[0:1], -1, v75
	s_and_b64 s[6:7], vcc, s[36:37]
	s_and_b64 s[6:7], s[6:7], s[0:1]
	s_and_saveexec_b64 s[0:1], s[6:7]
	ds_write_b32 v73, v101 offset:10240
	s_or_b64 exec, exec, s[0:1]
	v_add_u32_e32 v76, 0x2c00, v4
	v_ashrrev_i32_e32 v75, 8, v76
	v_add_u32_e32 v75, v14, v75
	v_cmp_gt_i32_e32 vcc, s67, v76
	v_cmp_gt_i32_e64 s[36:37], s68, v75
	v_cmp_lt_i32_e64 s[0:1], -1, v75
	s_and_b64 s[6:7], vcc, s[36:37]
	s_and_b64 s[6:7], s[6:7], s[0:1]
	s_and_saveexec_b64 s[0:1], s[6:7]
	ds_write_b32 v73, v102 offset:12288
	s_or_b64 exec, exec, s[0:1]
	v_add_u32_e32 v76, 0x2e00, v4
	v_ashrrev_i32_e32 v75, 8, v76
	v_add_u32_e32 v75, v14, v75
	v_cmp_gt_i32_e32 vcc, s67, v76
	v_cmp_gt_i32_e64 s[36:37], s68, v75
	v_cmp_lt_i32_e64 s[0:1], -1, v75
	s_and_b64 s[6:7], vcc, s[36:37]
	s_and_b64 s[6:7], s[6:7], s[0:1]
	s_and_saveexec_b64 s[0:1], s[6:7]
	ds_write_b32 v73, v103 offset:14336
	s_or_b64 exec, exec, s[0:1]
	v_add_u32_e32 v73, 0x4000, v73
	v_add_u32_e32 v76, 0x3000, v4
	v_ashrrev_i32_e32 v75, 8, v76
	v_add_u32_e32 v75, v14, v75
	v_cmp_gt_i32_e32 vcc, s67, v76
	v_cmp_gt_i32_e64 s[36:37], s68, v75
	v_cmp_lt_i32_e64 s[0:1], -1, v75
	s_and_b64 s[6:7], vcc, s[36:37]
	s_and_b64 s[6:7], s[6:7], s[0:1]
	s_and_saveexec_b64 s[0:1], s[6:7]
	ds_write_b32 v73, v104
	s_or_b64 exec, exec, s[0:1]
	v_add_u32_e32 v76, 0x3200, v4
	v_ashrrev_i32_e32 v75, 8, v76
	v_add_u32_e32 v75, v14, v75
	v_cmp_gt_i32_e32 vcc, s67, v76
	v_cmp_gt_i32_e64 s[36:37], s68, v75
	v_cmp_lt_i32_e64 s[0:1], -1, v75
	s_and_b64 s[6:7], vcc, s[36:37]
	s_and_b64 s[6:7], s[6:7], s[0:1]
	s_and_saveexec_b64 s[0:1], s[6:7]
	ds_write_b32 v73, v105 offset:2048
	s_or_b64 exec, exec, s[0:1]
	v_add_u32_e32 v76, 0x3400, v4
	v_ashrrev_i32_e32 v75, 8, v76
	v_add_u32_e32 v75, v14, v75
	v_cmp_gt_i32_e32 vcc, s67, v76
	v_cmp_gt_i32_e64 s[36:37], s68, v75
	v_cmp_lt_i32_e64 s[0:1], -1, v75
	s_and_b64 s[6:7], vcc, s[36:37]
	s_and_b64 s[6:7], s[6:7], s[0:1]
	s_and_saveexec_b64 s[0:1], s[6:7]
	ds_write_b32 v73, v106 offset:4096
	s_or_b64 exec, exec, s[0:1]
	v_add_u32_e32 v76, 0x3600, v4
	v_ashrrev_i32_e32 v75, 8, v76
	v_add_u32_e32 v75, v14, v75
	v_cmp_gt_i32_e32 vcc, s67, v76
	v_cmp_gt_i32_e64 s[36:37], s68, v75
	v_cmp_lt_i32_e64 s[0:1], -1, v75
	s_and_b64 s[6:7], vcc, s[36:37]
	s_and_b64 s[6:7], s[6:7], s[0:1]
	s_and_saveexec_b64 s[0:1], s[6:7]
	ds_write_b32 v73, v107 offset:6144
; __global__ void __launch_bounds__(NWAVES * 64, 2) mega_fwd(Args args) {
;     ...
; #pragma unroll 8
;                     for (int it = 0; it < 40; ++it) { const int e = tidp + it * 512; const int r = e >> 8, cq = e & 255, sr_ = s0 - 8 + r;
;                         if (e < 79 * 256 && sr_ >= 0 && sr_ < S_) ubuf[e] = *(const unsigned*)(sq + (size_t)sr_ * INC + 2 * cq); }
	s_or_b64 exec, exec, s[0:1]
	v_add_u32_e32 v76, 0x3800, v4
	v_ashrrev_i32_e32 v75, 8, v76
	v_add_u32_e32 v75, v14, v75
	v_cmp_gt_i32_e32 vcc, s67, v76
	v_cmp_gt_i32_e64 s[36:37], s68, v75
	v_cmp_lt_i32_e64 s[0:1], -1, v75
	s_and_b64 s[6:7], vcc, s[36:37]
	s_and_b64 s[6:7], s[6:7], s[0:1]
	s_and_saveexec_b64 s[0:1], s[6:7]
	ds_write_b32 v73, v108 offset:8192
	s_or_b64 exec, exec, s[0:1]
	v_add_u32_e32 v76, 0x3a00, v4
	v_ashrrev_i32_e32 v75, 8, v76
	v_add_u32_e32 v75, v14, v75
	v_cmp_gt_i32_e32 vcc, s67, v76
	v_cmp_gt_i32_e64 s[36:37], s68, v75
	v_cmp_lt_i32_e64 s[0:1], -1, v75
	s_and_b64 s[6:7], vcc, s[36:37]
	s_and_b64 s[6:7], s[6:7], s[0:1]
	s_and_saveexec_b64 s[0:1], s[6:7]
	ds_write_b32 v73, v109 offset:10240
	s_or_b64 exec, exec, s[0:1]
	v_add_u32_e32 v76, 0x3c00, v4
	v_ashrrev_i32_e32 v75, 8, v76
	v_add_u32_e32 v75, v14, v75
	v_cmp_gt_i32_e32 vcc, s67, v76
	v_cmp_gt_i32_e64 s[36:37], s68, v75
	v_cmp_lt_i32_e64 s[0:1], -1, v75
	s_and_b64 s[6:7], vcc, s[36:37]
	s_and_b64 s[6:7], s[6:7], s[0:1]
	s_and_saveexec_b64 s[0:1], s[6:7]
	ds_write_b32 v73, v110 offset:12288
	s_or_b64 exec, exec, s[0:1]
	v_add_u32_e32 v76, 0x3e00, v4
	v_ashrrev_i32_e32 v75, 8, v76
	v_add_u32_e32 v75, v14, v75
	v_cmp_gt_i32_e32 vcc, s67, v76
	v_cmp_gt_i32_e64 s[36:37], s68, v75
	v_cmp_lt_i32_e64 s[0:1], -1, v75
	s_and_b64 s[6:7], vcc, s[36:37]
	s_and_b64 s[6:7], s[6:7], s[0:1]
	s_and_saveexec_b64 s[0:1], s[6:7]
	ds_write_b32 v73, v111 offset:14336
	s_or_b64 exec, exec, s[0:1]
	v_add_u32_e32 v73, 0x4000, v73
	v_add_u32_e32 v76, 0x4000, v4
	v_ashrrev_i32_e32 v75, 8, v76
	v_add_u32_e32 v75, v14, v75
	v_cmp_gt_i32_e32 vcc, s67, v76
	v_cmp_gt_i32_e64 s[36:37], s68, v75
	v_cmp_lt_i32_e64 s[0:1], -1, v75
	s_and_b64 s[6:7], vcc, s[36:37]
	s_and_b64 s[6:7], s[6:7], s[0:1]
	s_and_saveexec_b64 s[0:1], s[6:7]
	ds_write_b32 v73, v112
	s_or_b64 exec, exec, s[0:1]
	v_add_u32_e32 v76, 0x4200, v4
	v_ashrrev_i32_e32 v75, 8, v76
	v_add_u32_e32 v75, v14, v75
	v_cmp_gt_i32_e32 vcc, s67, v76
	v_cmp_gt_i32_e64 s[36:37], s68, v75
	v_cmp_lt_i32_e64 s[0:1], -1, v75
	s_and_b64 s[6:7], vcc, s[36:37]
	s_and_b64 s[6:7], s[6:7], s[0:1]
	s_and_saveexec_b64 s[0:1], s[6:7]
	ds_write_b32 v73, v113 offset:2048
	s_or_b64 exec, exec, s[0:1]
	v_add_u32_e32 v76, 0x4400, v4
	v_ashrrev_i32_e32 v75, 8, v76
	v_add_u32_e32 v75, v14, v75
	v_cmp_gt_i32_e32 vcc, s67, v76
	v_cmp_gt_i32_e64 s[36:37], s68, v75
	v_cmp_lt_i32_e64 s[0:1], -1, v75
	s_and_b64 s[6:7], vcc, s[36:37]
	s_and_b64 s[6:7], s[6:7], s[0:1]
	s_and_saveexec_b64 s[0:1], s[6:7]
	ds_write_b32 v73, v114 offset:4096
	s_or_b64 exec, exec, s[0:1]
	v_add_u32_e32 v76, 0x4600, v4
	v_ashrrev_i32_e32 v75, 8, v76
	v_add_u32_e32 v75, v14, v75
	v_cmp_gt_i32_e32 vcc, s67, v76
	v_cmp_gt_i32_e64 s[36:37], s68, v75
	v_cmp_lt_i32_e64 s[0:1], -1, v75
	s_and_b64 s[6:7], vcc, s[36:37]
	s_and_b64 s[6:7], s[6:7], s[0:1]
	s_and_saveexec_b64 s[0:1], s[6:7]
	ds_write_b32 v73, v115 offset:6144
	s_or_b64 exec, exec, s[0:1]
	v_add_u32_e32 v76, 0x4800, v4
	v_ashrrev_i32_e32 v75, 8, v76
	v_add_u32_e32 v75, v14, v75
	v_cmp_gt_i32_e32 vcc, s67, v76
	v_cmp_gt_i32_e64 s[36:37], s68, v75
	v_cmp_lt_i32_e64 s[0:1], -1, v75
	s_and_b64 s[6:7], vcc, s[36:37]
	s_and_b64 s[6:7], s[6:7], s[0:1]
	s_and_saveexec_b64 s[0:1], s[6:7]
	ds_write_b32 v73, v132 offset:8192
	s_or_b64 exec, exec, s[0:1]
	v_add_u32_e32 v76, 0x4a00, v4
	v_ashrrev_i32_e32 v75, 8, v76
	v_add_u32_e32 v75, v14, v75
	v_cmp_gt_i32_e32 vcc, s67, v76
	v_cmp_gt_i32_e64 s[36:37], s68, v75
	v_cmp_lt_i32_e64 s[0:1], -1, v75
	s_and_b64 s[6:7], vcc, s[36:37]
	s_and_b64 s[6:7], s[6:7], s[0:1]
	s_and_saveexec_b64 s[0:1], s[6:7]
	ds_write_b32 v73, v133 offset:10240
	s_or_b64 exec, exec, s[0:1]
	v_add_u32_e32 v76, 0x4c00, v4
	v_ashrrev_i32_e32 v75, 8, v76
	v_add_u32_e32 v75, v14, v75
	v_cmp_gt_i32_e32 vcc, s67, v76
	v_cmp_gt_i32_e64 s[36:37], s68, v75
	v_cmp_lt_i32_e64 s[0:1], -1, v75
	s_and_b64 s[6:7], vcc, s[36:37]
	s_and_b64 s[6:7], s[6:7], s[0:1]
	s_and_saveexec_b64 s[0:1], s[6:7]
	ds_write_b32 v73, v134 offset:12288
	s_or_b64 exec, exec, s[0:1]
	v_add_u32_e32 v76, 0x4e00, v4
	v_ashrrev_i32_e32 v75, 8, v76
	v_add_u32_e32 v75, v14, v75
	v_cmp_gt_i32_e32 vcc, s67, v76
	v_cmp_gt_i32_e64 s[36:37], s68, v75
	v_cmp_lt_i32_e64 s[0:1], -1, v75
	s_and_b64 s[6:7], vcc, s[36:37]
	s_and_b64 s[6:7], s[6:7], s[0:1]
	s_and_saveexec_b64 s[0:1], s[6:7]
	ds_write_b32 v73, v135 offset:14336
	s_or_b64 exec, exec, s[0:1]
	v_add_u32_e32 v73, 0x4000, v73
	s_movk_i32 s4, 0x5000
